# P2 rebalance v2: B-only workgroups 10 units each, compression workgroups take the last 128 units (2 each)
# speedup vs baseline: 1.0095x; 1.0016x over previous
; __global__ void __launch_bounds__(512, 2) fwd_mega(Params P) {
;     ...
;         if (G > 64) {
;             if (bx < 64) { for (int j = 0; j < 4; ++j) { const int u = bx * 4 + j, qb = u & 63, bh = u >> 6; b_unit(Z, MIX, P.in[12], lds, bh >> 1, bh & 1, qb, gt, wave0); } }
;             else { for (int u = 256 + (bx - 64); u < 2048; u += G - 64) { const int qb = u & 63, bh = u >> 6; b_unit(Z, MIX, P.in[12], lds, bh >> 1, bh & 1, qb, gt, wave0); } }
;         } else { for (int u = bx; u < 2048; u += G) { const int qb = u & 63, bh = u >> 6; b_unit(Z, MIX, P.in[12], lds, bh >> 1, bh & 1, qb, gt, wave0); } }
.LBB0_492:
	s_and_b64 vcc, exec, s[84:85]
	s_cmpk_gt_u32 s89, 0x73f
	s_mov_b32 s3, 0
	s_cbranch_scc1 .LBB0_550
	s_mov_b32 s69, 0
	s_mov_b32 s68, s69
	s_mov_b32 s70, s69
	s_mov_b32 s71, s69
	s_mov_b32 s72, s69
	s_mov_b32 s73, s69
	s_mov_b32 s74, s69
	s_mov_b32 s75, s69
	s_mov_b32 s76, s69
	s_mov_b32 s77, s69
	s_mov_b32 s78, s69
	s_mov_b32 s79, s69
	s_mov_b32 s80, s69
	s_mov_b32 s81, s69
	s_mov_b32 s82, s69
	s_mov_b32 s83, s69
	v_mov_b64_e32 v[0:1], s[68:69]
	s_add_i32 s2, s89, -64
	s_sub_i32 s33, s94, 64
	s_movk_i32 s99, 0x77f
	s_cmp_gt_i32 s89, 63
	s_cbranch_scc1 .Lb_cls_done
	s_add_i32 s2, s89, 0x780
	s_movk_i32 s33, 64
	s_movk_i32 s99, 0x7ff
.Lb_cls_done:
	s_movk_i32 s84, 0x1600
	v_mov_b64_e32 v[160:161], s[86:87]
	v_mov_b32_e32 v163, 0
	v_mov_b64_e32 v[2:3], s[70:71]
	v_mov_b64_e32 v[4:5], s[72:73]
	v_mov_b64_e32 v[6:7], s[74:75]
	v_mov_b64_e32 v[8:9], s[76:77]
	v_mov_b64_e32 v[10:11], s[78:79]
	v_mov_b64_e32 v[12:13], s[80:81]
	v_mov_b64_e32 v[14:15], s[82:83]
	s_mov_b32 s76, 0xff800000
	s_mov_b32 s77, 0x40c00000
	v_mov_b32_e32 v170, 0x1600
	v_mov_b32_e32 v171, 0xff800000
	s_mov_b32 s82, 0

; #define LAS __attribute__((address_space(3)))
; #define LDS_WAIT() asm volatile("s_waitcnt lgkmcnt(0)" ::: "memory")
; __device__ __forceinline__ unsigned pk2(float lo, float hi) { f32x2_t v = {lo, hi}; bf16x2_t b = __builtin_convertvector(v, bf16x2_t); return __builtin_bit_cast(unsigned, b); }
; __device__ __forceinline__ int crow(int r, int hi) { return (r & 3) + 8 * (r >> 2) + 4 * hi; }
; #define GAS __attribute__((address_space(1)))
; __device__ __forceinline__ void rows_axpy(f32x16 (&acc)[2], const f32x16 (&o)[2], float f, LAS float* wsf, int r32, int hi, bool init) {
;     LDS_WAIT();
;     if (hi == 0) wsf[r32] = f;
;     LDS_WAIT();
; #pragma unroll
;     for (int r = 0; r < 16; ++r) { const float g = wsf[crow(r, hi)];
;         if (init) { acc[0][r] = o[0][r] * g; acc[1][r] = o[1][r] * g; } else { acc[0][r] += o[0][r] * g; acc[1][r] += o[1][r] * g; } }
;     LDS_WAIT();
; }
; template <class F> __device__ __forceinline__ void stage_store(const f32x16 (&ot)[2], ldsp lds, int w, int lane, int r32, int hi, F rowp) {
;     LAS float* stg = (LAS float*)(lds + 65536 + w * 8704);
; #pragma unroll
;     for (int d0 = 0; d0 < 2; ++d0)
; #pragma unroll
;         for (int r = 0; r < 16; ++r) stg[crow(r, hi) * 68 + d0 * 32 + r32] = ot[d0][r];
;     LDS_WAIT();
; #pragma unroll
;     for (int i = 0; i < 4; ++i) {
;         const int row = i * 8 + (lane >> 3);
;         const f32x4 x0 = *(const LAS f32x4*)(stg + row * 68 + (lane & 7) * 8), x1 = *(const LAS f32x4*)(stg + row * 68 + (lane & 7) * 8 + 4);
;         u32x4 ow; ow.x = pk2(x0[0], x0[1]); ow.y = pk2(x0[2], x0[3]); ow.z = pk2(x1[0], x1[1]); ow.w = pk2(x1[2], x1[3]);
;         *(GAS u32x4*)(rowp(row) + (lane & 7) * 8) = ow;
;     }
;     LDS_WAIT();
; __global__ void __launch_bounds__(512, 2) fwd_mega(Params P) {
;     ...
;             else { for (int u = 256 + (bx - 64); u < 2048; u += G - 64) { const int qb = u & 63, bh = u >> 6; b_unit(Z, MIX, P.in[12], lds, bh >> 1, bh & 1, qb, gt, wave0); } }
.LBB0_546:
	s_or_b64 exec, exec, s[6:7]
	s_waitcnt lgkmcnt(0)
	v_add_u32_e32 v56, s68, v164
	ds_read_b128 v[48:51], v56
	ds_read_b128 v[52:55], v56 offset:32
	s_mulk_i32 s73, 0x2200
	s_add_i32 s4, s73, 0
	s_add_i32 s4, s4, 0x10000
	s_waitcnt lgkmcnt(1)
	v_mul_f32_e32 v57, v16, v48
	v_mul_f32_e32 v32, v32, v48
	v_mul_f32_e32 v48, v17, v49
	v_mul_f32_e32 v33, v33, v49
	v_mul_f32_e32 v49, v18, v50
	v_mul_f32_e32 v34, v34, v50
	v_mul_f32_e32 v50, v19, v51
	ds_read_b128 v[16:19], v56 offset:64
	v_mul_f32_e32 v35, v35, v51
	s_waitcnt lgkmcnt(1)
	v_mul_f32_e32 v51, v20, v52
	v_mul_f32_e32 v36, v36, v52
	v_mul_f32_e32 v52, v21, v53
	v_mul_f32_e32 v37, v37, v53
	v_mul_f32_e32 v53, v22, v54
	v_mul_f32_e32 v38, v38, v54
	v_mul_f32_e32 v54, v23, v55
	ds_read_b128 v[20:23], v56 offset:96
	s_waitcnt lgkmcnt(1)
	v_mul_f32_e32 v24, v24, v16
	v_mul_f32_e32 v16, v40, v16
	v_mul_f32_e32 v25, v25, v17
	v_mul_f32_e32 v17, v41, v17
	v_lshlrev_b32_e32 v40, 2, v167
	v_mul_u32_u24_e32 v41, 0x440, v172
	v_add3_u32 v40, s4, v40, v41
	s_waitcnt lgkmcnt(0)
	ds_write2_b32 v40, v57, v32 offset1:32
	ds_write2_b32 v40, v48, v33 offset0:68 offset1:100
	ds_write2_b32 v40, v49, v34 offset0:136 offset1:168
	ds_write2_b32 v40, v50, v35 offset0:204 offset1:236
	v_add_u32_e32 v32, 0x800, v40
	v_mul_f32_e32 v39, v39, v55
	ds_write2_b32 v32, v51, v36 offset0:32 offset1:64
	ds_write2_b32 v32, v52, v37 offset0:100 offset1:132
	ds_write2_b32 v32, v53, v38 offset0:168 offset1:200
	v_add_u32_e32 v32, 0xa00, v40
	ds_write2_b32 v32, v54, v39 offset0:108 offset1:140
	v_add_u32_e32 v32, 0x1000, v40
	v_mul_f32_e32 v26, v26, v18
	v_mul_f32_e32 v18, v42, v18
	v_mul_f32_e32 v27, v27, v19
	v_mul_f32_e32 v19, v43, v19
	ds_write2_b32 v32, v24, v16 offset0:64 offset1:96
	ds_write2_b32 v32, v25, v17 offset0:132 offset1:164
	ds_write2_b32 v32, v26, v18 offset0:200 offset1:232
	v_add_u32_e32 v16, 0x1400, v40
	s_waitcnt lgkmcnt(11)
	v_mul_f32_e32 v28, v28, v20
	v_mul_f32_e32 v20, v44, v20
	ds_write2_b32 v16, v27, v19 offset0:12 offset1:44
	v_add_u32_e32 v16, 0x1800, v40
	v_mul_f32_e32 v29, v29, v21
	v_mul_f32_e32 v21, v45, v21
	v_mul_f32_e32 v30, v30, v22
	v_mul_f32_e32 v22, v46, v22
	ds_write2_b32 v16, v28, v20 offset0:96 offset1:128
	ds_write2_b32 v16, v29, v21 offset0:164 offset1:196
	v_add_u32_e32 v16, 0x1a00, v40
	v_mul_f32_e32 v31, v31, v23
	v_mul_f32_e32 v23, v47, v23
	ds_write2_b32 v16, v30, v22 offset0:104 offset1:136
	v_add_u32_e32 v16, 0x1c00, v40
	v_lshrrev_b32_e32 v18, 3, v165
	ds_write2_b32 v16, v31, v23 offset0:44 offset1:76
	v_or_b32_e32 v16, s79, v18
	s_ashr_i32 s73, s72, 31
	v_or_b32_e32 v16, s70, v16
	v_mov_b32_e32 v17, s71
	v_and_b32_e32 v26, 56, v174
	v_lshl_add_u64 v[16:17], v[16:17], 0, s[72:73]
	v_lshlrev_b32_e32 v19, 2, v26
	v_lshlrev_b64 v[20:21], 11, v[16:17]
	v_mul_u32_u24_e32 v16, 0x110, v18
	s_waitcnt lgkmcnt(0)
	v_add3_u32 v28, s4, v19, v16
	ds_read_b128 v[16:19], v28
	v_lshl_add_u64 v[24:25], s[0:1], 0, v[20:21]
	ds_read_b128 v[20:23], v28 offset:16
	v_lshlrev_b32_e32 v162, 1, v26
	v_lshl_add_u64 v[24:25], v[24:25], 0, v[162:163]
	s_waitcnt lgkmcnt(1)
	v_cvt_pk_bf16_f32 v16, v16, v17
	v_cvt_pk_bf16_f32 v17, v18, v19
	s_waitcnt lgkmcnt(0)
	v_cvt_pk_bf16_f32 v18, v20, v21
	v_cvt_pk_bf16_f32 v19, v22, v23
	ds_read_b128 v[20:23], v28 offset:2176
	s_lshl_b32 s68, s78, 9
	v_lshl_add_u64 v[32:33], v[24:25], 0, s[68:69]
	ds_read_b128 v[24:27], v28 offset:2192
	global_store_dwordx4 v[32:33], v[16:19], off offset:1024
	s_add_i32 s2, s33, s2
	s_cmp_gt_i32 s2, s99
	s_waitcnt lgkmcnt(1)
	v_cvt_pk_bf16_f32 v16, v20, v21
	v_cvt_pk_bf16_f32 v17, v22, v23
	ds_read_b128 v[20:23], v28 offset:4352
	s_waitcnt lgkmcnt(1)
	v_cvt_pk_bf16_f32 v18, v24, v25
	v_cvt_pk_bf16_f32 v19, v26, v27
	ds_read_b128 v[24:27], v28 offset:4368
	global_store_dwordx4 v[32:33], v[16:19], off offset:1152
	s_waitcnt lgkmcnt(1)
	s_nop 0
	v_cvt_pk_bf16_f32 v16, v20, v21
	v_cvt_pk_bf16_f32 v17, v22, v23
	ds_read_b128 v[20:23], v28 offset:6528
	ds_read_b128 v[28:31], v28 offset:6544
	s_waitcnt lgkmcnt(2)
	v_cvt_pk_bf16_f32 v18, v24, v25
	v_cvt_pk_bf16_f32 v19, v26, v27
	global_store_dwordx4 v[32:33], v[16:19], off offset:1280
	s_waitcnt lgkmcnt(1)
	s_nop 0
	v_cvt_pk_bf16_f32 v16, v20, v21
	v_cvt_pk_bf16_f32 v17, v22, v23
	s_waitcnt lgkmcnt(0)
	v_cvt_pk_bf16_f32 v18, v28, v29
	v_cvt_pk_bf16_f32 v19, v30, v31
	global_store_dwordx4 v[32:33], v[16:19], off offset:1408
	s_waitcnt lgkmcnt(0)
	s_cbranch_scc1 .LBB0_549
	s_mov_b32 s82, s3
	s_branch .LBB0_495
